# v23 + nt on the P3 gate-array (G) stores, consumed only in P4c
# speedup vs baseline: 1.0039x; 1.0015x over previous
; __device__ __forceinline__ unsigned pk2(float lo, float hi) { f32x2_t v = {lo, hi}; bf16x2_t b = __builtin_convertvector(v, bf16x2_t); return __builtin_bit_cast(unsigned, b); }
; __device__ __forceinline__ float sigmoidf_(float x) { return __builtin_amdgcn_rcpf(1.0f + __expf(-x)); }
; __device__ __forceinline__ f32x4 bf4(u32x2 w) { return (f32x4){__uint_as_float(w.x << 16), __uint_as_float(w.x & 0xffff0000u), __uint_as_float(w.y << 16), __uint_as_float(w.y & 0xffff0000u)}; }
; __device__ __forceinline__ void phase3(const P3Args& A, unsigned char* lds, int tid, int wave, int lane) {
;     ...
;                 const f32x4 w0 = *(const f32x4*)(A.w0 + ch), a0 = *(const f32x4*)(A.a0 + ch), ka = *(const f32x4*)(A.k_a + ch), rk = *(const f32x4*)(A.r_k + ch);
;                 const f32x4 mur = *(const f32x4*)(A.mu + ch), muk = *(const f32x4*)(A.mu + 512 + ch), muv = *(const f32x4*)(A.mu + 1024 + ch);
;                 const unsigned char* rs = stg + fr * 144 + c4 * 2;
;                 const f32x4 r0 = bf4(*(const u32x2*)(rs)), r1 = bf4(*(const u32x2*)(rs + 144));
;                 const f32x4 k0 = bf4(*(const u32x2*)(rs + 17 * 144)), k1 = bf4(*(const u32x2*)(rs + 18 * 144));
;                 const f32x4 v0 = bf4(*(const u32x2*)(rs + 34 * 144)), v1 = bf4(*(const u32x2*)(rs + 35 * 144));
;                 const f32x4 rm = r1 + (r0 - r1) * mur, km = k1 + (k0 - k1) * muk, vm = v1 + (v0 - v1) * muv;
;                 f32x4 lw, ah;
; #pragma unroll
;                 for (int r = 0; r < 4; ++r) { lw[r] = -0.6065306597f * sigmoidf_(w0[r] + ad[r]); ah[r] = sigmoidf_(a0[r] + ai[r]); }
;                 const f32x4 kp = km * ((ah - 1.0f) * ka + 1.0f);
;                 const f32x4 pr3 = rm * kp * rk;
;                 float rks = (pr3[0] + pr3[1]) + (pr3[2] + pr3[3]);
;                 rks = rows4_sum(rks);
;                 if (fq == 0) RK[((size_t)t * 8 + wave) * 4 + ct] = rks;
;                 lwo[ct] = lw;
;                 ro[ct] = (u32x2){pk2(rm[0], rm[1]), pk2(rm[2], rm[3])}; ko[ct] = (u32x2){pk2(km[0], km[1]), pk2(km[2], km[3])};
;                 vo[ct] = (u32x2){pk2(vm[0], vm[1]), pk2(vm[2], vm[3])}; aho[ct] = (u32x2){pk2(ah[0], ah[1]), pk2(ah[2], ah[3])};
;                 go[ct] = (u32x2){pk2(ag[0], ag[1]), pk2(ag[2], ag[3])};
.LBB0_336:
	s_or_b64 exec, exec, s[0:1]
	s_waitcnt lgkmcnt(0)
	v_lshlrev_b32_e32 v110, 16, v104
	v_and_b32_e32 v118, 0xffff0000, v104
	v_lshlrev_b32_e32 v120, 16, v105
	v_and_b32_e32 v122, 0xffff0000, v105
	v_lshlrev_b32_e32 v104, 16, v106
	v_and_b32_e32 v105, 0xffff0000, v106
	v_sub_f32_e32 v119, v118, v105
	v_sub_f32_e32 v118, v110, v104
	s_waitcnt vmcnt(0)
	v_pk_fma_f32 v[100:101], v[100:101], v[118:119], v[104:105]
	v_cvt_pk_bf16_f32 v88, v88, v89
	v_cvt_pk_bf16_f32 v89, v90, v91
	v_lshlrev_b32_e32 v90, 16, v68
	v_and_b32_e32 v91, 0xffff0000, v68
	v_lshlrev_b32_e32 v110, 16, v69
	v_and_b32_e32 v118, 0xffff0000, v69
	v_lshlrev_b32_e32 v68, 16, v70
	v_and_b32_e32 v69, 0xffff0000, v70
	v_lshlrev_b32_e32 v70, 16, v71
	v_and_b32_e32 v71, 0xffff0000, v71
	v_sub_f32_e32 v91, v91, v69
	v_sub_f32_e32 v90, v90, v68
	v_sub_f32_e32 v119, v118, v71
	v_sub_f32_e32 v118, v110, v70
	v_pk_fma_f32 v[64:65], v[64:65], v[90:91], v[68:69]
	v_pk_fma_f32 v[118:119], v[66:67], v[118:119], v[70:71]
	v_cvt_pk_bf16_f32 v66, v64, v65
	v_add_f32_e32 v64, v80, v84
	v_mul_f32_e32 v64, 0xbfb8aa3b, v64
	v_exp_f32_e32 v68, v64
	v_add_f32_e32 v69, v82, v86
	v_mul_f32_e32 v69, 0xbfb8aa3b, v69
	v_exp_f32_e32 v69, v69
	v_add_f32_e32 v68, 1.0, v68
	v_rcp_f32_e32 v80, v68
	v_add_f32_e32 v68, v81, v85
	v_add_f32_e32 v81, v83, v87
	v_mul_f32_e32 v68, 0xbfb8aa3b, v68
	v_mul_f32_e32 v81, 0xbfb8aa3b, v81
	v_exp_f32_e32 v68, v68
	v_exp_f32_e32 v81, v81
	v_add_f32_e32 v69, 1.0, v69
	v_rcp_f32_e32 v82, v69
	v_add_f32_e32 v68, 1.0, v68
	v_add_f32_e32 v69, 1.0, v81
	v_rcp_f32_e32 v83, v69
	v_rcp_f32_e32 v81, v68
	v_cvt_pk_bf16_f32 v68, v56, v57
	v_cvt_pk_bf16_f32 v69, v58, v59
	v_pk_mul_f32 v[58:59], v[82:83], s[38:39] op_sel_hi:[1,0]
	v_pk_mul_f32 v[56:57], v[80:81], s[38:39] op_sel_hi:[1,0]
	v_lshlrev_b32_e32 v80, 16, v36
	v_and_b32_e32 v81, 0xffff0000, v36
	v_lshlrev_b32_e32 v82, 16, v37
	v_and_b32_e32 v83, 0xffff0000, v37
	v_lshlrev_b32_e32 v36, 16, v38
	v_and_b32_e32 v37, 0xffff0000, v38
	v_sub_f32_e32 v81, v81, v37
	v_sub_f32_e32 v80, v80, v36
	v_pk_fma_f32 v[32:33], v[32:33], v[80:81], v[36:37]
	v_add_f32_e32 v45, v53, v45
	v_cvt_pk_bf16_f32 v32, v32, v33
	v_add_f32_e32 v33, v52, v44
	v_add_f32_e32 v46, v54, v46
	v_add_f32_e32 v47, v55, v47
	v_mul_f32_e32 v33, 0xbfb8aa3b, v33
	v_mul_f32_e32 v45, 0xbfb8aa3b, v45
	v_mul_f32_e32 v46, 0xbfb8aa3b, v46
	v_mul_f32_e32 v47, 0xbfb8aa3b, v47
	v_exp_f32_e32 v44, v33
	v_exp_f32_e32 v45, v45
	v_exp_f32_e32 v46, v46
	v_exp_f32_e32 v47, v47
	v_add_f32_e32 v44, 1.0, v44
	v_add_f32_e32 v45, 1.0, v45
	v_add_f32_e32 v46, 1.0, v46
	v_add_f32_e32 v47, 1.0, v47
	v_rcp_f32_e32 v44, v44
	v_rcp_f32_e32 v46, v46
	v_rcp_f32_e32 v47, v47
	v_rcp_f32_e32 v45, v45
	v_cvt_pk_bf16_f32 v55, v10, v11
	v_add_f32_e32 v11, v27, v23
	v_add_f32_e32 v0, v4, v0
	v_cvt_pk_bf16_f32 v52, v28, v29
	v_cvt_pk_bf16_f32 v53, v30, v31
	v_pk_mul_f32 v[30:31], v[46:47], s[38:39] op_sel_hi:[1,0]
	v_pk_mul_f32 v[28:29], v[44:45], s[38:39] op_sel_hi:[1,0]
	v_lshlrev_b32_e32 v44, 16, v16
	v_and_b32_e32 v45, 0xffff0000, v16
	v_lshlrev_b32_e32 v46, 16, v17
	v_and_b32_e32 v47, 0xffff0000, v17
	v_lshlrev_b32_e32 v16, 16, v18
	v_and_b32_e32 v17, 0xffff0000, v18
	v_mul_f32_e32 v11, 0xbfb8aa3b, v11
	v_mul_f32_e32 v0, 0xbfb8aa3b, v0
	v_sub_f32_e32 v45, v45, v17
	v_sub_f32_e32 v44, v44, v16
	v_exp_f32_e32 v11, v11
	v_exp_f32_e32 v0, v0
	v_pk_fma_f32 v[12:13], v[12:13], v[44:45], v[16:17]
	v_cvt_pk_bf16_f32 v54, v8, v9
	v_cvt_pk_bf16_f32 v44, v12, v13
	v_add_f32_e32 v12, v24, v20
	v_add_f32_e32 v9, v25, v21
	v_mul_f32_e32 v12, 0xbfb8aa3b, v12
	v_mul_f32_e32 v9, 0xbfb8aa3b, v9
	v_exp_f32_e32 v12, v12
	v_exp_f32_e32 v9, v9
	v_add_f32_e32 v4, 1.0, v11
	v_add_f32_e32 v0, 1.0, v0
	v_rcp_f32_e32 v11, v4
	v_rcp_f32_e32 v4, v0
	v_add_f32_e32 v0, v5, v1
	v_add_f32_e32 v1, v6, v2
	v_mul_f32_e32 v1, 0xbfb8aa3b, v1
	v_add_f32_e32 v2, v7, v3
	v_add_f32_e32 v10, v26, v22
	v_mul_f32_e32 v0, 0xbfb8aa3b, v0
	v_exp_f32_e32 v1, v1
	v_mul_f32_e32 v2, 0xbfb8aa3b, v2
	v_add_f32_e32 v8, 1.0, v12
	v_mul_f32_e32 v10, 0xbfb8aa3b, v10
	v_add_f32_e32 v9, 1.0, v9
	v_exp_f32_e32 v0, v0
	v_exp_f32_e32 v2, v2
	v_exp_f32_e32 v10, v10
	v_rcp_f32_e32 v8, v8
	v_rcp_f32_e32 v9, v9
	v_add_f32_e32 v1, 1.0, v1
	v_add_f32_e32 v0, 1.0, v0
	v_rcp_f32_e32 v6, v1
	v_add_f32_e32 v1, 1.0, v2
	v_add_f32_e32 v10, 1.0, v10
	v_rcp_f32_e32 v7, v1
	v_rcp_f32_e32 v5, v0
	v_pk_mul_f32 v[0:1], v[8:9], s[38:39] op_sel_hi:[1,0]
	v_ashrrev_i32_e32 v8, 3, v116
	v_lshlrev_b32_e32 v106, 16, v107
	v_and_b32_e32 v107, 0xffff0000, v107
	v_rcp_f32_e32 v10, v10
	v_mul_lo_u32 v9, v8, s3
	v_sub_f32_e32 v155, v122, v107
	v_sub_f32_e32 v154, v120, v106
	v_cvt_pk_bf16_f32 v36, v148, v149
	v_cvt_pk_bf16_f32 v37, v146, v147
	v_lshlrev_b32_e32 v18, 16, v19
	v_and_b32_e32 v19, 0xffff0000, v19
	v_cvt_pk_bf16_f32 v16, v134, v135
	v_cvt_pk_bf16_f32 v17, v136, v137
	v_add3_u32 v22, s39, v129, v9
	v_ashrrev_i32_e32 v9, 31, v8
	v_pk_fma_f32 v[154:155], v[102:103], v[154:155], v[106:107]
	v_cvt_pk_bf16_f32 v106, v174, v175
	v_cvt_pk_bf16_f32 v107, v172, v173
	v_cvt_pk_bf16_f32 v90, v162, v163
	v_cvt_pk_bf16_f32 v91, v160, v161
	v_sub_f32_e32 v47, v47, v19
	v_sub_f32_e32 v46, v46, v18
	s_waitcnt lgkmcnt(0)
; #define LDS_WAIT() asm volatile("s_waitcnt lgkmcnt(0)" ::: "memory")
; __device__ __forceinline__ void phase3(const P3Args& A, unsigned char* lds, int tid, int wave, int lane) {
;     ...
;             P3_ROWLOAD((tt < 7) ? tt + 1 : 7, ln);
;             LDS_WAIT();
;             const size_t ob = hb + (size_t)(tt * 16) * 64;
;     ...
;             P3_STAGE_BF16(Rr, ro); P3_STAGE_BF16(Kr, ko); P3_STAGE_BF16(Vr, vo); P3_STAGE_BF16(AH, aho); P3_STAGE_BF16(G, go);
;     ...
;             {
; #pragma unroll
;                 for (int ct = 0; ct < 4; ++ct) *(f32x4*)(stg + fr * 272 + (ct * 16 + fq * 4) * 4) = lwo[ct];
;                 LDS_WAIT();
; #pragma unroll
;                 for (int j = 0; j < 4; ++j) { const int tk = (ln >> 4) + 4 * j, c4 = (ln & 15) * 4;
;                     const f32x4 v = *(const f32x4*)(stg + tk * 272 + c4 * 4); *(f32x4*)(LW + ob + (size_t)tk * 64 + c4) = v; }
;                 LDS_WAIT();
;             }
	ds_write2_b64 v182, v[16:17], v[36:37] offset1:4
	ds_write2_b64 v182, v[90:91], v[106:107] offset0:8 offset1:12
	v_lshlrev_b64 v[8:9], 7, v[8:9]
	s_add_u32 s0, s28, s8
	v_pk_fma_f32 v[14:15], v[14:15], v[46:47], v[18:19]
	s_waitcnt lgkmcnt(0)
	v_or_b32_e32 v8, v8, v129
	s_addc_u32 s1, s29, s9
	v_cvt_pk_bf16_f32 v45, v14, v15
	v_pk_mul_f32 v[2:3], v[10:11], s[38:39] op_sel_hi:[1,0]
	v_lshl_add_u64 v[16:17], s[0:1], 0, v[8:9]
	ds_read_b128 v[8:11], v22
	ds_read_b128 v[12:15], v22 offset:1152
	s_mov_b32 s0, 0x11800000
	v_lshlrev_b32_e32 v38, 16, v39
	v_and_b32_e32 v39, 0xffff0000, v39
	v_add_co_u32_e64 v20, s[0:1], s0, v16
	v_sub_f32_e32 v83, v83, v39
	v_sub_f32_e32 v82, v82, v38
	v_addc_co_u32_e64 v21, s[0:1], 0, v17, s[0:1]
	v_pk_fma_f32 v[34:35], v[34:35], v[82:83], v[38:39]
	v_cvt_pk_bf16_f32 v38, v152, v153
	v_cvt_pk_bf16_f32 v39, v150, v151
	v_cvt_pk_bf16_f32 v18, v138, v139
	v_cvt_pk_bf16_f32 v19, v140, v141
	s_waitcnt lgkmcnt(1)
	global_store_dwordx4 v[20:21], v[8:11], off
	s_waitcnt lgkmcnt(0)
	global_store_dwordx4 v[20:21], v[12:15], off offset:1024
	v_cvt_pk_bf16_f32 v104, v178, v179
	v_cvt_pk_bf16_f32 v105, v176, v177
	v_cvt_pk_bf16_f32 v70, v166, v167
	v_cvt_pk_bf16_f32 v71, v164, v165
	s_waitcnt lgkmcnt(0)
	ds_write2_b64 v182, v[18:19], v[38:39] offset1:4
	ds_write2_b64 v182, v[70:71], v[104:105] offset0:8 offset1:12
	s_waitcnt lgkmcnt(0)
	ds_read_b128 v[8:11], v22
	ds_read_b128 v[12:15], v22 offset:1152
	s_mov_b32 s0, 0x13800000
	v_add_co_u32_e64 v18, s[0:1], s0, v16
	v_cvt_pk_bf16_f32 v33, v34, v35
	s_nop 0
	v_addc_co_u32_e64 v19, s[0:1], 0, v17, s[0:1]
	s_waitcnt lgkmcnt(1)
	global_store_dwordx4 v[18:19], v[8:11], off
	s_waitcnt lgkmcnt(0)
	global_store_dwordx4 v[18:19], v[12:15], off offset:1024
	v_cvt_pk_bf16_f32 v102, v100, v101
	v_cvt_pk_bf16_f32 v103, v154, v155
	v_cvt_pk_bf16_f32 v67, v118, v119
	s_waitcnt lgkmcnt(0)
	ds_write2_b64 v182, v[44:45], v[32:33] offset1:4
	ds_write2_b64 v182, v[66:67], v[102:103] offset0:8 offset1:12
	s_waitcnt lgkmcnt(0)
	ds_read_b128 v[8:11], v22
	ds_read_b128 v[12:15], v22 offset:1152
	s_mov_b32 s0, 0x15800000
	v_add_co_u32_e64 v18, s[0:1], s0, v16
	v_cvt_pk_bf16_f32 v34, v142, v143
	s_nop 0
	v_addc_co_u32_e64 v19, s[0:1], 0, v17, s[0:1]
	v_cvt_pk_bf16_f32 v35, v144, v145
	v_cvt_pk_bf16_f32 v46, v130, v131
	v_cvt_pk_bf16_f32 v47, v132, v133
	s_waitcnt lgkmcnt(1)
	global_store_dwordx4 v[18:19], v[8:11], off
	s_waitcnt lgkmcnt(0)
	global_store_dwordx4 v[18:19], v[12:15], off offset:1024
	v_cvt_pk_bf16_f32 v100, v168, v169
	v_cvt_pk_bf16_f32 v101, v170, v171
	v_cvt_pk_bf16_f32 v64, v156, v157
	v_cvt_pk_bf16_f32 v65, v158, v159
	s_waitcnt lgkmcnt(0)
	ds_write2_b64 v182, v[46:47], v[34:35] offset1:4
	ds_write2_b64 v182, v[64:65], v[100:101] offset0:8 offset1:12
	s_waitcnt lgkmcnt(0)
	ds_read_b128 v[8:11], v22
	ds_read_b128 v[12:15], v22 offset:1152
	s_mov_b32 s0, 0x4800000
	v_add_co_u32_e64 v18, s[0:1], s0, v16
	v_pk_mul_f32 v[6:7], v[6:7], s[38:39] op_sel_hi:[1,0]
	s_nop 0
	v_addc_co_u32_e64 v19, s[0:1], 0, v17, s[0:1]
	s_waitcnt lgkmcnt(1)
	global_store_dwordx4 v[18:19], v[8:11], off
	s_waitcnt lgkmcnt(0)
	global_store_dwordx4 v[18:19], v[12:15], off offset:1024
	s_waitcnt lgkmcnt(0)
	ds_write2_b64 v182, v[54:55], v[52:53] offset1:4
	ds_write2_b64 v182, v[68:69], v[88:89] offset0:8 offset1:12
	s_waitcnt lgkmcnt(0)
	ds_read_b128 v[8:11], v22
	ds_read_b128 v[12:15], v22 offset:1152
	s_mov_b32 s0, 0x2800000
	v_add_co_u32_e64 v16, s[0:1], s0, v16
	v_pk_mul_f32 v[4:5], v[4:5], s[38:39] op_sel_hi:[1,0]
	s_nop 0
	v_addc_co_u32_e64 v17, s[0:1], 0, v17, s[0:1]
	s_waitcnt lgkmcnt(1)
	global_store_dwordx4 v[16:17], v[8:11], off nt
	s_waitcnt lgkmcnt(0)
	global_store_dwordx4 v[16:17], v[12:15], off offset:1024 nt
	s_waitcnt lgkmcnt(0)
	s_add_u32 s0, s28, s10
	v_mul_lo_u32 v8, v180, s2
	v_add3_u32 v8, s39, v8, v181
	ds_write_b128 v8, v[4:7]
	ds_write_b128 v8, v[0:3] offset:64
	ds_write_b128 v8, v[28:31] offset:128
	ds_write_b128 v8, v[56:59] offset:192
	v_ashrrev_i32_e32 v0, 4, v116
	v_and_b32_e32 v1, 0xf0, v127
	v_mul_lo_u32 v2, v0, s2
	v_add3_u32 v12, s39, v1, v2
	v_ashrrev_i32_e32 v1, 31, v0
	v_lshlrev_b64 v[0:1], 8, v[0:1]
	v_and_b32_e32 v2, 15, v116
	s_waitcnt lgkmcnt(0)
	v_lshl_or_b32 v0, v2, 4, v0
	s_addc_u32 s1, s29, s11
	v_lshl_add_u64 v[16:17], s[0:1], 0, v[0:1]
	ds_read_b128 v[0:3], v12
	ds_read_b128 v[4:7], v12 offset:1088
	ds_read_b128 v[8:11], v12 offset:2176
	ds_read_b128 v[12:15], v12 offset:3264
	s_mov_b32 s0, 0x17800000
	v_add_co_u32_e64 v16, s[0:1], s0, v16
	s_add_i32 s12, s12, 16
	s_nop 0
	v_addc_co_u32_e64 v17, s[0:1], 0, v17, s[0:1]
	s_add_u32 s8, s8, 0x800
	s_waitcnt lgkmcnt(3)
	global_store_dwordx4 v[16:17], v[0:3], off
	s_waitcnt lgkmcnt(2)
	global_store_dwordx4 v[16:17], v[4:7], off offset:1024
	s_waitcnt lgkmcnt(1)
	global_store_dwordx4 v[16:17], v[8:11], off offset:2048
	s_waitcnt lgkmcnt(0)
	global_store_dwordx4 v[16:17], v[12:15], off offset:3072
	s_addc_u32 s9, s9, 0
	s_add_u32 s10, s10, 0x1000
	s_waitcnt lgkmcnt(0)
	s_addc_u32 s11, s11, 0
	s_cmpk_eq_i32 s12, 0x90
	s_cbranch_scc1 .LBB0_310
